# attention: V staging loads coalesced (K-like lane pattern), LDS transpose writes re-addressed
# speedup vs baseline: 1.0159x; 1.0159x over previous
.LBB0_1164:
	s_or_b64 exec, exec, s[0:1]
	v_mov_b32_e32 v1, v168
	v_readlane_b32 s12, v243, 21
	s_waitcnt lgkmcnt(0)
	s_barrier
	v_readlane_b32 s13, v243, 22
	v_and_b32_e32 v0, 63, v1
	v_readlane_b32 s14, v243, 23
	v_readlane_b32 s15, v243, 24
	v_readlane_b32 s16, v243, 25
	v_readlane_b32 s17, v243, 26
	v_lshlrev_b32_e32 v2, 2, v0
	v_readlane_b32 s18, v243, 27
	v_readlane_b32 s19, v243, 28
	v_readlane_b32 s20, v243, 29
	v_readlane_b32 s21, v243, 30
	s_mov_b64 s[12:13], s[16:17]
	s_mov_b64 s[14:15], s[18:19]
	global_load_dword v3, v2, s[12:13]
	global_load_dword v4, v2, s[14:15]
	v_mbcnt_hi_u32_b32 v2, -1, v169
	v_and_b32_e32 v5, 64, v2
	v_xor_b32_e32 v6, 1, v2
	v_add_u32_e32 v5, 64, v5
	v_cmp_lt_i32_e32 vcc, v6, v5
	v_xor_b32_e32 v7, 2, v2
	v_xor_b32_e32 v8, 4, v2
	v_cndmask_b32_e32 v6, v2, v6, vcc
	v_lshlrev_b32_e32 v6, 2, v6
	v_cmp_lt_i32_e32 vcc, v7, v5
	v_xor_b32_e32 v9, 8, v2
	v_xor_b32_e32 v10, 16, v2
	v_cndmask_b32_e32 v7, v2, v7, vcc
	v_lshlrev_b32_e32 v7, 2, v7
	v_cmp_lt_i32_e32 vcc, v8, v5
	v_xor_b32_e32 v11, 32, v2
	s_cmpk_lt_i32 s69, 0x800
	v_cndmask_b32_e32 v8, v2, v8, vcc
	v_lshlrev_b32_e32 v8, 2, v8
	v_cmp_lt_i32_e32 vcc, v9, v5
	s_mov_b32 s7, 0
	v_readlane_b32 s22, v243, 31
	v_readlane_b32 s23, v243, 32
	v_readlane_b32 s24, v243, 33
	v_readlane_b32 s25, v243, 34
	v_readlane_b32 s26, v243, 35
	v_readlane_b32 s27, v243, 36
	s_mov_b64 s[16:17], s[20:21]
	s_waitcnt vmcnt(1)
	v_and_b32_e32 v12, 0x7fffffff, v3
	s_waitcnt vmcnt(0)
	v_and_b32_e32 v13, 0x7fffffff, v4
	ds_bpermute_b32 v12, v6, v12
	ds_bpermute_b32 v6, v6, v13
	v_max_f32_e64 v3, |v3|, |v3|
	v_max_f32_e64 v4, |v4|, |v4|
	s_waitcnt lgkmcnt(1)
	v_max_f32_e32 v12, v12, v12
	s_waitcnt lgkmcnt(0)
	v_max_f32_e32 v6, v6, v6
	v_max_f32_e32 v3, v3, v12
	v_max_f32_e32 v4, v4, v6
	ds_bpermute_b32 v6, v7, v3
	ds_bpermute_b32 v7, v7, v4
	s_waitcnt lgkmcnt(1)
	v_max_f32_e32 v6, v6, v6
	s_waitcnt lgkmcnt(0)
	v_max_f32_e32 v7, v7, v7
	v_max_f32_e32 v3, v3, v6
	v_max_f32_e32 v4, v4, v7
	ds_bpermute_b32 v6, v8, v3
	ds_bpermute_b32 v7, v8, v4
	v_cndmask_b32_e32 v8, v2, v9, vcc
	v_lshlrev_b32_e32 v8, 2, v8
	v_cmp_lt_i32_e32 vcc, v10, v5
	s_waitcnt lgkmcnt(1)
	v_max_f32_e32 v6, v6, v6
	s_waitcnt lgkmcnt(0)
	v_max_f32_e32 v7, v7, v7
	v_max_f32_e32 v3, v3, v6
	v_max_f32_e32 v4, v4, v7
	ds_bpermute_b32 v6, v8, v3
	ds_bpermute_b32 v7, v8, v4
	v_cndmask_b32_e32 v8, v2, v10, vcc
	v_lshlrev_b32_e32 v169, 2, v8
	v_cmp_lt_i32_e32 vcc, v11, v5
	s_waitcnt lgkmcnt(1)
	v_max_f32_e32 v6, v6, v6
	s_waitcnt lgkmcnt(0)
	v_max_f32_e32 v7, v7, v7
	v_max_f32_e32 v3, v3, v6
	v_max_f32_e32 v4, v4, v7
	ds_bpermute_b32 v6, v169, v3
	ds_bpermute_b32 v7, v169, v4
	v_cndmask_b32_e32 v2, v2, v11, vcc
	v_lshlrev_b32_e32 v202, 2, v2
	s_waitcnt lgkmcnt(1)
	v_max_f32_e32 v2, v6, v6
	s_waitcnt lgkmcnt(0)
	v_max_f32_e32 v5, v7, v7
	v_max_f32_e32 v3, v3, v2
	v_max_f32_e32 v2, v4, v5
	ds_bpermute_b32 v5, v202, v3
	ds_bpermute_b32 v4, v202, v2
	s_cbranch_scc0 .LBB0_1203
	s_waitcnt lgkmcnt(1)
	v_max_f32_e32 v5, v5, v5
	v_max_f32_e32 v3, v3, v3
	v_max_f32_e32 v3, v3, v5
	s_waitcnt lgkmcnt(0)
	v_max_f32_e32 v4, v4, v4
	v_max_f32_e32 v2, v2, v2
	v_max_f32_e32 v2, v2, v4
	v_lshrrev_b32_e32 v174, 5, v0
	v_mul_f32_e32 v0, 0xc138aa3b, v3
	v_and_b32_e32 v149, 31, v1
	v_mul_f32_e32 v0, v2, v0
	v_ashrrev_i32_e32 v175, 7, v1
	v_and_b32_e32 v176, 64, v1
	v_ashrrev_i32_e32 v177, 2, v1
	v_lshlrev_b32_e32 v2, 4, v1
	v_and_b32_e32 v148, 0x7f, v1
	v_ashrrev_i32_e32 v1, 4, v1
	s_movk_i32 s0, 0x48
	v_and_b32_e32 v150, -8, v1
	v_mul_lo_u32 v1, v177, s0
	s_movk_i32 s0, 0x84
	v_mov_b32_e32 v145, 0
	v_readlane_b32 s2, v243, 56
	s_nop 0
	v_lshlrev_b32_e32 v16, 4, v174
	v_mov_b32_e32 v17, v145
	v_readlane_b32 s3, v243, 57
	v_readlane_b32 s0, v243, 54
	v_lshlrev_b32_e32 v144, 3, v174
	v_lshl_add_u64 v[146:147], s[2:3], 0, v[16:17]
	v_lshlrev_b32_e32 v17, 2, v174
	v_readlane_b32 s1, v243, 55
	v_or_b32_e32 v19, 1, v17
	v_and_b32_e32 v18, 48, v2
	v_mul_u32_u24_e32 v152, 0x84, v18
	v_add_u32_e32 v152, v152, v177
	v_lshl_add_u64 v[154:155], s[0:1], 0, v[144:145]
	v_cmp_ge_u32_e64 s[0:1], v17, v149
	v_ashrrev_i32_e32 v151, 31, v150
	v_lshlrev_b32_e32 v178, 1, v1
	v_writelane_b32 v242, s0, 3
	v_lshlrev_b32_e32 v20, 1, v18
	v_lshrrev_b32_e32 v180, 5, v176
	v_writelane_b32 v242, s1, 4
	v_cmp_le_u32_e64 s[0:1], v17, v149
	v_or_b32_e32 v1, 32, v149
	v_mov_b32_e32 v21, v145
	v_writelane_b32 v242, s0, 5
	v_add3_u32 v179, 0, v178, v20
	v_lshl_add_u32 v153, v152, 1, 0
	v_writelane_b32 v242, s1, 6
	v_cmp_ge_u32_e64 s[0:1], v19, v149
	v_or_b32_e32 v19, 2, v17
	v_cvt_f32_ubyte0_e32 v181, v149
	v_writelane_b32 v242, s0, 7
	v_cvt_f32_ubyte0_e32 v182, v1
	v_mov_b32_e32 v1, v0
	v_writelane_b32 v242, s1, 8
	v_cmp_lt_u32_e64 s[0:1], v17, v149
	v_mov_b32_e32 v2, v0
	v_mov_b32_e32 v3, v0
	v_writelane_b32 v242, s0, 9
	v_mov_b32_e32 v4, v0
	v_mov_b32_e32 v5, v0
	v_writelane_b32 v242, s1, 10
	v_cmp_ge_u32_e64 s[0:1], v19, v149
	v_mov_b32_e32 v6, v0
	v_mov_b32_e32 v7, v0
	v_writelane_b32 v242, s0, 11
	v_mov_b32_e32 v8, v0
	v_mov_b32_e32 v9, v0
	v_writelane_b32 v242, s1, 12
	v_cmp_le_u32_e64 s[0:1], v19, v149
	v_or_b32_e32 v19, 3, v17
	v_mov_b32_e32 v10, v0
	v_writelane_b32 v242, s0, 13
	v_mov_b32_e32 v11, v0
	v_mov_b32_e32 v12, v0
	v_writelane_b32 v242, s1, 14
	v_cmp_ge_u32_e64 s[0:1], v19, v149
	v_mov_b32_e32 v13, v0
	v_mov_b32_e32 v14, v0
	v_writelane_b32 v242, s0, 15
	v_mov_b32_e32 v15, v0
	v_or_b32_e32 v183, 1, v180
	v_writelane_b32 v242, s1, 16
	v_cmp_le_u32_e64 s[0:1], v19, v149
	v_or_b32_e32 v19, 8, v17
	v_lshl_add_u64 v[156:157], s[2:3], 0, v[20:21]
	v_writelane_b32 v243, s0, 43
	v_lshl_add_u64 v[158:159], v[150:151], 1, s[2:3]
	v_mov_b32_e32 v186, 0x358637bd
	v_writelane_b32 v243, s1, 44
	v_cmp_ge_u32_e64 s[0:1], v19, v149
	s_nop 1
	v_writelane_b32 v243, s0, 37
	s_nop 1
	v_writelane_b32 v243, s1, 38
	v_cmp_le_u32_e64 s[0:1], v19, v149
	v_or_b32_e32 v19, 9, v17
	s_nop 0
	v_writelane_b32 v243, s0, 39
	s_nop 1
	v_writelane_b32 v243, s1, 40
	v_cmp_ge_u32_e64 s[0:1], v19, v149
	s_nop 1
	v_writelane_b32 v243, s0, 52
	s_nop 1
	v_writelane_b32 v243, s1, 53
	v_cmp_le_u32_e64 s[0:1], v19, v149
	v_or_b32_e32 v19, 10, v17
	v_cmp_le_u32_e64 s[30:31], v19, v149
	v_writelane_b32 v242, s0, 1
	s_nop 1
	v_writelane_b32 v242, s1, 2
	v_cmp_ge_u32_e64 s[0:1], v19, v149
	v_or_b32_e32 v19, 11, v17
	v_cmp_ge_u32_e64 s[34:35], v19, v149
	v_cmp_le_u32_e64 s[36:37], v19, v149
	v_or_b32_e32 v19, 16, v17
	v_cmp_ge_u32_e64 s[38:39], v19, v149
	v_cmp_le_u32_e64 s[40:41], v19, v149
	v_or_b32_e32 v19, 17, v17
	v_cmp_ge_u32_e64 s[42:43], v19, v149
	v_cmp_le_u32_e64 s[44:45], v19, v149
	v_or_b32_e32 v19, 18, v17
	v_cmp_ge_u32_e64 s[46:47], v19, v149
	v_cmp_le_u32_e64 s[48:49], v19, v149
	v_or_b32_e32 v19, 19, v17
	v_cmp_ge_u32_e64 s[50:51], v19, v149
	v_cmp_le_u32_e64 s[52:53], v19, v149
	v_or_b32_e32 v19, 24, v17
	v_cmp_ge_u32_e64 s[54:55], v19, v149
	v_cmp_le_u32_e64 s[56:57], v19, v149
	v_or_b32_e32 v19, 25, v17
	v_writelane_b32 v243, s0, 41
	v_cmp_ge_u32_e64 s[58:59], v19, v149
	v_cmp_le_u32_e64 s[60:61], v19, v149
	v_or_b32_e32 v19, 26, v17
	v_or_b32_e32 v17, 27, v17
	v_writelane_b32 v243, s1, 42
	v_cmp_ge_u32_e64 s[66:67], v17, v149
	s_mov_b32 s0, s69
	v_cmp_le_u32_e64 s[68:69], v17, v149
	v_mul_u32_u24_e32 v17, 0x108, v149
	v_add3_u32 v17, v17, v144, 0
	v_readlane_b32 s12, v243, 21
	v_add_u32_e32 v184, 0x4800, v17
	v_mul_u32_u24_e32 v17, 0x90, v149
	v_readlane_b32 s13, v243, 22
	v_readlane_b32 s16, v243, 25
	v_readlane_b32 s17, v243, 26
	v_cmp_ge_u32_e64 s[62:63], v19, v149
	v_cmp_le_u32_e64 s[64:65], v19, v149
	v_add3_u32 v185, v17, v16, 0
	v_lshlrev_b32_e32 v144, 1, v18
	s_mov_b32 s11, s0
	s_mov_b64 s[12:13], s[16:17]
	v_readlane_b32 s14, v243, 23
	v_readlane_b32 s15, v243, 24
	v_readlane_b32 s18, v243, 27
	v_readlane_b32 s19, v243, 28
	v_readlane_b32 s20, v243, 29
	v_readlane_b32 s21, v243, 30
	v_readlane_b32 s22, v243, 31
	v_readlane_b32 s23, v243, 32
	v_readlane_b32 s24, v243, 33
	v_readlane_b32 s25, v243, 34
	v_readlane_b32 s26, v243, 35
	v_readlane_b32 s27, v243, 36
	s_branch .LBB0_1167

.LBB0_1167:
	s_bfe_u32 s1, s11, 0x20006
	s_lshl_b32 s0, s11, 7
	v_lshl_add_u32 v164, s1, 2, v175
	s_and_b32 s0, s0, 0x1f80
	s_lshl_b32 s2, s11, 5
	v_lshlrev_b32_e32 v162, 6, v164
	v_or_b32_e32 v18, s0, v176
	s_and_b32 s2, s2, 0xffffe000
	v_ashrrev_i32_e32 v163, 31, v162
	v_lshl_add_u64 v[64:65], v[162:163], 1, v[146:147]
	v_or3_b32 v160, s2, v149, v18
	s_movk_i32 s10, 0xc00
	v_mov_b32_e32 v16, v174
	v_lshrrev_b32_e32 v48, 6, v18
	v_mad_i64_i32 v[18:19], s[4:5], v160, s10, v[64:65]
	global_load_dwordx4 v[84:87], v[18:19], off
	global_load_dwordx4 v[88:91], v[18:19], off offset:32
	global_load_dwordx4 v[94:97], v[18:19], off offset:64
	global_load_dwordx4 v[98:101], v[18:19], off offset:96
	v_lshlrev_b32_e32 v60, 3, v16
	v_ashrrev_i32_e32 v61, 31, v60
	v_lshl_add_u64 v[16:17], v[60:61], 2, s[12:13]
	global_load_dwordx4 v[44:47], v[16:17], off
	global_load_dwordx4 v[40:43], v[16:17], off offset:16
	global_load_dwordx4 v[36:39], v[16:17], off offset:64
	global_load_dwordx4 v[32:35], v[16:17], off offset:80
	v_cvt_f32_i32_e32 v18, v60
	v_or_b32_e32 v51, 2, v60
	v_cvt_f32_i32_e32 v51, v51
	v_cvt_f32_ubyte0_e32 v61, v48
	v_mul_f32_e32 v18, 0xbf549a78, v18
	v_exp_f32_e32 v49, v18
	global_load_dwordx4 v[28:31], v[16:17], off offset:128
	global_load_dwordx4 v[24:27], v[16:17], off offset:144
	global_load_dwordx4 v[20:23], v[16:17], off offset:192
	s_nop 0
	global_load_dwordx4 v[16:19], v[16:17], off offset:208
	v_mul_f32_e32 v51, 0xbf549a78, v51
	v_exp_f32_e32 v53, v51
	v_mul_f32_e32 v165, 0.15915494, v49
	v_or_b32_e32 v49, 1, v60
	v_cvt_f32_i32_e32 v49, v49
	v_or_b32_e32 v57, 5, v60
	v_cvt_f32_i32_e32 v57, v57
	v_mul_f32_e32 v171, 0.15915494, v53
	v_mul_f32_e32 v49, 0xbf549a78, v49
	v_exp_f32_e32 v49, v49
	v_mul_f32_e32 v53, v171, v61
	v_mul_f32_e32 v57, 0xbf549a78, v57
	v_or_b32_e32 v59, 6, v60
	v_mul_f32_e32 v170, 0.15915494, v49
	v_mul_f32_e32 v52, v170, v61
	v_cos_f32_e32 v49, v52
	v_sin_f32_e32 v51, v52
	v_or_b32_e32 v52, 3, v60
	v_cvt_f32_i32_e32 v54, v52
	v_cos_f32_e32 v52, v53
	v_exp_f32_e32 v57, v57
	v_cvt_f32_i32_e32 v59, v59
	v_mul_f32_e32 v54, 0xbf549a78, v54
	v_exp_f32_e32 v55, v54
	v_sin_f32_e32 v54, v53
	v_or_b32_e32 v53, 4, v60
	v_cvt_f32_i32_e32 v56, v53
	v_mul_f32_e32 v187, 0.15915494, v57
	v_mul_f32_e32 v57, 0xbf549a78, v59
	v_exp_f32_e32 v63, v57
	v_mul_f32_e32 v56, 0xbf549a78, v56
	v_exp_f32_e32 v56, v56
	v_or_b32_e32 v57, 7, v60
	v_cvt_f32_i32_e32 v60, v57
	v_mul_f32_e32 v50, v165, v61
	v_mul_f32_e32 v172, 0.15915494, v55
	v_cos_f32_e32 v48, v50
	v_sin_f32_e32 v50, v50
	v_mul_f32_e32 v55, v172, v61
	v_mul_f32_e32 v173, 0.15915494, v56
	v_cos_f32_e32 v53, v55
	v_sin_f32_e32 v55, v55
	v_mul_f32_e32 v58, v173, v61
	v_mul_f32_e32 v62, v187, v61
	v_cos_f32_e32 v56, v58
	v_sin_f32_e32 v58, v58
	v_cos_f32_e32 v57, v62
	v_sin_f32_e32 v59, v62
	v_mul_f32_e32 v60, 0xbf549a78, v60
	v_mul_f32_e32 v92, 0.15915494, v63
	v_exp_f32_e32 v63, v60
	v_or_b32_e32 v166, 32, v160
	v_mad_i64_i32 v[64:65], s[4:5], v166, s10, v[64:65]
	v_mul_f32_e32 v93, 0.15915494, v63
	v_mul_f32_e32 v62, v92, v61
	v_mul_f32_e32 v63, v93, v61
	v_cos_f32_e32 v60, v62
	v_cos_f32_e32 v61, v63
	v_sin_f32_e32 v62, v62
	v_sin_f32_e32 v63, v63
	v_mul_f32_e32 v67, v165, v181
	v_mul_f32_e32 v68, v170, v181
	v_cos_f32_e32 v66, v67
	v_sin_f32_e32 v70, v67
	s_waitcnt vmcnt(11)
	v_lshlrev_b32_e32 v140, 16, v84
	v_and_b32_e32 v141, 0xffff0000, v84
	v_lshlrev_b32_e32 v132, 16, v85
	v_and_b32_e32 v133, 0xffff0000, v85
	v_pk_mul_f32 v[84:85], v[140:141], v[140:141]
	v_pk_mul_f32 v[134:135], v[132:133], v[132:133]
	v_add_f32_e32 v84, v84, v85
	v_lshlrev_b32_e32 v128, 16, v86
	v_and_b32_e32 v129, 0xffff0000, v86
	v_add_f32_e32 v84, v134, v84
	v_lshlrev_b32_e32 v120, 16, v87
	v_and_b32_e32 v121, 0xffff0000, v87
	v_pk_mul_f32 v[86:87], v[128:129], v[128:129]
	v_add_f32_e32 v84, v135, v84
	v_add_f32_e32 v84, v86, v84
	v_pk_mul_f32 v[122:123], v[120:121], v[120:121]
	v_add_f32_e32 v84, v87, v84
	s_waitcnt vmcnt(10)
	v_lshlrev_b32_e32 v142, 16, v88
	v_and_b32_e32 v143, 0xffff0000, v88
	v_add_f32_e32 v84, v122, v84
	v_lshlrev_b32_e32 v136, 16, v89
	v_and_b32_e32 v137, 0xffff0000, v89
	v_pk_mul_f32 v[88:89], v[142:143], v[142:143]
	v_add_f32_e32 v84, v123, v84
	v_add_f32_e32 v84, v88, v84
	v_pk_mul_f32 v[138:139], v[136:137], v[136:137]
	v_add_f32_e32 v84, v89, v84
	v_lshlrev_b32_e32 v130, 16, v90
	v_and_b32_e32 v131, 0xffff0000, v90
	v_add_f32_e32 v84, v138, v84
	v_lshlrev_b32_e32 v124, 16, v91
	v_and_b32_e32 v125, 0xffff0000, v91
	v_pk_mul_f32 v[90:91], v[130:131], v[130:131]
	v_add_f32_e32 v84, v139, v84
	v_add_f32_e32 v84, v90, v84
	v_pk_mul_f32 v[126:127], v[124:125], v[124:125]
	v_add_f32_e32 v84, v91, v84
	s_waitcnt vmcnt(9)
	v_lshlrev_b32_e32 v114, 16, v94
	v_and_b32_e32 v115, 0xffff0000, v94
	v_add_f32_e32 v84, v126, v84
	v_lshlrev_b32_e32 v108, 16, v95
	v_and_b32_e32 v109, 0xffff0000, v95
	v_pk_mul_f32 v[94:95], v[114:115], v[114:115]
	v_add_f32_e32 v84, v127, v84
	v_add_f32_e32 v84, v94, v84
	v_pk_mul_f32 v[110:111], v[108:109], v[108:109]
	v_add_f32_e32 v84, v95, v84
	v_lshlrev_b32_e32 v106, 16, v96
	v_and_b32_e32 v107, 0xffff0000, v96
	v_add_f32_e32 v84, v110, v84
	v_lshlrev_b32_e32 v80, 16, v97
	v_and_b32_e32 v81, 0xffff0000, v97
	v_pk_mul_f32 v[96:97], v[106:107], v[106:107]
	v_add_f32_e32 v84, v111, v84
	v_add_f32_e32 v84, v96, v84
	v_pk_mul_f32 v[102:103], v[80:81], v[80:81]
	v_add_f32_e32 v84, v97, v84
	s_waitcnt vmcnt(8)
	v_lshlrev_b32_e32 v118, 16, v98
	v_and_b32_e32 v119, 0xffff0000, v98
	v_add_f32_e32 v84, v102, v84
	v_lshlrev_b32_e32 v116, 16, v99
	v_and_b32_e32 v117, 0xffff0000, v99
	v_pk_mul_f32 v[98:99], v[118:119], v[118:119]
	v_add_f32_e32 v84, v103, v84
	v_add_f32_e32 v84, v98, v84
	v_pk_mul_f32 v[112:113], v[116:117], v[116:117]
	v_add_f32_e32 v84, v99, v84
	v_lshlrev_b32_e32 v82, 16, v100
	v_and_b32_e32 v83, 0xffff0000, v100
	v_add_f32_e32 v84, v112, v84
	v_lshlrev_b32_e32 v78, 16, v101
	v_and_b32_e32 v79, 0xffff0000, v101
	v_pk_mul_f32 v[100:101], v[82:83], v[82:83]
	v_add_f32_e32 v84, v113, v84
	v_add_f32_e32 v84, v100, v84
	v_pk_mul_f32 v[104:105], v[78:79], v[78:79]
	v_add_f32_e32 v84, v101, v84
	v_add_f32_e32 v84, v104, v84
	v_add_f32_e32 v85, v105, v84
	ds_bpermute_b32 v87, v202, v85
	v_cos_f32_e32 v67, v68
	v_sin_f32_e32 v71, v68
	v_mul_f32_e32 v69, v171, v181
	v_mul_f32_e32 v72, v172, v181
	s_waitcnt lgkmcnt(0)
	v_add_f32_e32 v85, v85, v87
	v_fmamk_f32 v85, v85, 0x3c800000, v186
	v_rsq_f32_e32 v88, v85
	v_cos_f32_e32 v68, v69
	v_sin_f32_e32 v74, v69
	v_cos_f32_e32 v69, v72
	v_mul_f32_e32 v94, 0x3e38aa3b, v88
	s_waitcnt vmcnt(7)
	v_pk_mul_f32 v[88:89], v[44:45], v[94:95] op_sel_hi:[1,0]
	s_waitcnt vmcnt(1)
	v_pk_mul_f32 v[122:123], v[20:21], v[94:95] op_sel_hi:[1,0]
	v_pk_mul_f32 v[96:97], v[88:89], v[140:141]
	v_pk_mul_f32 v[88:89], v[46:47], v[94:95] op_sel_hi:[1,0]
	v_pk_mul_f32 v[112:113], v[26:27], v[94:95] op_sel_hi:[1,0]
	v_pk_mul_f32 v[98:99], v[88:89], v[132:133]
	v_pk_mul_f32 v[88:89], v[40:41], v[94:95] op_sel_hi:[1,0]
	v_pk_mul_f32 v[80:81], v[112:113], v[80:81]
	v_pk_mul_f32 v[100:101], v[88:89], v[128:129]
	v_pk_mul_f32 v[88:89], v[42:43], v[94:95] op_sel_hi:[1,0]
	v_pk_mul_f32 v[128:129], v[122:123], v[118:119]
	v_pk_mul_f32 v[102:103], v[88:89], v[120:121]
	v_pk_mul_f32 v[88:89], v[36:37], v[94:95] op_sel_hi:[1,0]
	v_pk_mul_f32 v[118:119], v[22:23], v[94:95] op_sel_hi:[1,0]
	v_pk_mul_f32 v[104:105], v[88:89], v[142:143]
	v_pk_mul_f32 v[88:89], v[38:39], v[94:95] op_sel_hi:[1,0]
	v_sin_f32_e32 v75, v72
	v_pk_mul_f32 v[110:111], v[88:89], v[136:137]
	v_pk_mul_f32 v[88:89], v[32:33], v[94:95] op_sel_hi:[1,0]
	v_mul_f32_e32 v73, v173, v181
	v_pk_mul_f32 v[120:121], v[88:89], v[130:131]
	v_pk_mul_f32 v[88:89], v[34:35], v[94:95] op_sel_hi:[1,0]
	v_pk_mul_f32 v[130:131], v[118:119], v[116:117]
	v_pk_mul_f32 v[124:125], v[88:89], v[124:125]
	v_pk_mul_f32 v[88:89], v[28:29], v[94:95] op_sel_hi:[1,0]
	s_waitcnt vmcnt(0)
	v_pk_mul_f32 v[116:117], v[16:17], v[94:95] op_sel_hi:[1,0]
	v_pk_mul_f32 v[126:127], v[88:89], v[114:115]
	v_pk_mul_f32 v[88:89], v[30:31], v[94:95] op_sel_hi:[1,0]
	v_pk_mul_f32 v[82:83], v[116:117], v[82:83]
	v_pk_mul_f32 v[108:109], v[88:89], v[108:109]
	v_pk_mul_f32 v[88:89], v[24:25], v[94:95] op_sel_hi:[1,0]
	v_pk_mul_f32 v[94:95], v[18:19], v[94:95] op_sel_hi:[1,0]
	v_pk_mul_f32 v[116:117], v[58:59], v[120:121]
	v_pk_mul_f32 v[78:79], v[94:95], v[78:79]
	v_pk_mul_f32 v[94:95], v[48:49], v[104:105]
	v_pk_mul_f32 v[104:105], v[50:51], v[104:105]
	v_pk_fma_f32 v[94:95], v[50:51], v[96:97], v[94:95]
	v_pk_fma_f32 v[96:97], v[48:49], v[96:97], v[104:105] neg_lo:[0,0,1] neg_hi:[0,0,1]
	v_pk_mul_f32 v[104:105], v[52:53], v[110:111]
	v_pk_mul_f32 v[110:111], v[54:55], v[110:111]
	v_pk_fma_f32 v[104:105], v[54:55], v[98:99], v[104:105]
	v_pk_fma_f32 v[98:99], v[52:53], v[98:99], v[110:111] neg_lo:[0,0,1] neg_hi:[0,0,1]
	v_pk_mul_f32 v[110:111], v[56:57], v[120:121]
	v_pk_mul_f32 v[120:121], v[60:61], v[124:125]
	v_pk_fma_f32 v[110:111], v[58:59], v[100:101], v[110:111]
	v_pk_fma_f32 v[100:101], v[56:57], v[100:101], v[116:117] neg_lo:[0,0,1] neg_hi:[0,0,1]
	global_load_dwordx4 v[116:119], v[64:65], off
	v_pk_fma_f32 v[132:133], v[62:63], v[102:103], v[120:121]
	global_load_dwordx4 v[120:123], v[64:65], off offset:32
	v_pk_mul_f32 v[106:107], v[88:89], v[106:107]
	global_load_dwordx4 v[88:91], v[64:65], off offset:64
	global_load_dwordx4 v[112:115], v[64:65], off offset:96
	v_pk_mul_f32 v[64:65], v[62:63], v[124:125]
	v_mul_f32_e32 v77, v187, v181
	v_pk_fma_f32 v[64:65], v[60:61], v[102:103], v[64:65] neg_lo:[0,0,1] neg_hi:[0,0,1]
	v_pk_mul_f32 v[102:103], v[66:67], v[128:129]
	v_cos_f32_e32 v72, v73
	v_pk_fma_f32 v[124:125], v[70:71], v[126:127], v[102:103]
	v_pk_mul_f32 v[70:71], v[70:71], v[128:129]
	v_sin_f32_e32 v76, v73
	v_pk_fma_f32 v[66:67], v[66:67], v[126:127], v[70:71] neg_lo:[0,0,1] neg_hi:[0,0,1]
	v_pk_mul_f32 v[70:71], v[68:69], v[130:131]
	v_cos_f32_e32 v73, v77
	v_pk_fma_f32 v[70:71], v[74:75], v[108:109], v[70:71]
	v_pk_mul_f32 v[74:75], v[74:75], v[130:131]
	v_sin_f32_e32 v77, v77
	v_pk_fma_f32 v[68:69], v[68:69], v[108:109], v[74:75] neg_lo:[0,0,1] neg_hi:[0,0,1]
	v_cvt_pk_bf16_f32 v109, v70, v71
	v_mul_f32_e32 v70, v172, v182
	v_mul_f32_e32 v71, v173, v182
	v_mul_f32_e32 v86, v92, v181
	v_mul_f32_e32 v87, v93, v181
	v_cos_f32_e32 v84, v86
	v_sin_f32_e32 v86, v86
	v_cos_f32_e32 v85, v87
	v_sin_f32_e32 v87, v87
	v_pk_mul_f32 v[74:75], v[72:73], v[82:83]
	v_cvt_pk_bf16_f32 v96, v96, v97
	v_cvt_pk_bf16_f32 v97, v98, v99
	v_cvt_pk_bf16_f32 v98, v100, v101
	v_cvt_pk_bf16_f32 v101, v104, v105
	v_cvt_pk_bf16_f32 v104, v66, v67
	v_mul_f32_e32 v66, v170, v182
	v_mul_f32_e32 v67, v171, v182
	v_pk_fma_f32 v[74:75], v[76:77], v[106:107], v[74:75]
	v_pk_mul_f32 v[76:77], v[76:77], v[82:83]
	v_cvt_pk_bf16_f32 v103, v132, v133
	v_pk_fma_f32 v[72:73], v[72:73], v[106:107], v[76:77] neg_lo:[0,0,1] neg_hi:[0,0,1]
	v_pk_mul_f32 v[76:77], v[84:85], v[78:79]
	v_pk_mul_f32 v[78:79], v[86:87], v[78:79]
	v_pk_fma_f32 v[76:77], v[86:87], v[80:81], v[76:77]
	v_pk_fma_f32 v[78:79], v[84:85], v[80:81], v[78:79] neg_lo:[0,0,1] neg_hi:[0,0,1]
	v_cvt_pk_bf16_f32 v100, v94, v95
	v_cvt_pk_bf16_f32 v107, v78, v79
	v_cvt_pk_bf16_f32 v102, v110, v111
	v_cvt_pk_bf16_f32 v111, v76, v77
	v_cvt_pk_bf16_f32 v108, v124, v125
	s_cmp_eq_u32 s0, 0
	s_cselect_b64 s[4:5], -1, 0
	v_cvt_pk_bf16_f32 v99, v64, v65
	v_mul_f32_e32 v65, v165, v182
	v_cndmask_b32_e64 v165, 0, 1, s[4:5]
	s_and_b64 s[4:5], s[4:5], exec
	s_cselect_b32 s3, 0, 0xffffff80
	s_or_b32 s24, s2, s0
	s_add_i32 s4, s3, s24
	v_readlane_b32 s2, v243, 56
	v_readlane_b32 s3, v243, 57
	s_lshl_b32 s6, s1, 7
	s_barrier
	v_cvt_pk_bf16_f32 v105, v68, v69
	v_cos_f32_e32 v64, v65
	v_sin_f32_e32 v68, v65
	v_cos_f32_e32 v65, v66
	v_sin_f32_e32 v69, v66
	v_cvt_pk_bf16_f32 v106, v72, v73
	v_cvt_pk_bf16_f32 v110, v74, v75
	v_cos_f32_e32 v66, v67
	v_sin_f32_e32 v72, v67
	v_cos_f32_e32 v67, v70
	v_sin_f32_e32 v73, v70
	v_mul_f32_e32 v75, v187, v182
	v_cos_f32_e32 v70, v71
	v_sin_f32_e32 v74, v71
	s_waitcnt vmcnt(3)
	v_lshlrev_b32_e32 v194, 16, v116
	v_and_b32_e32 v195, 0xffff0000, v116
	v_lshlrev_b32_e32 v172, 16, v117
	v_and_b32_e32 v173, 0xffff0000, v117
	v_pk_mul_f32 v[116:117], v[194:195], v[194:195]
	v_pk_mul_f32 v[188:189], v[172:173], v[172:173]
	v_add_f32_e32 v116, v116, v117
	v_lshlrev_b32_e32 v142, 16, v118
	v_and_b32_e32 v143, 0xffff0000, v118
	v_add_f32_e32 v116, v188, v116
	v_lshlrev_b32_e32 v134, 16, v119
	v_and_b32_e32 v135, 0xffff0000, v119
	v_pk_mul_f32 v[118:119], v[142:143], v[142:143]
	v_add_f32_e32 v116, v189, v116
	v_add_f32_e32 v116, v118, v116
	v_pk_mul_f32 v[136:137], v[134:135], v[134:135]
	v_add_f32_e32 v116, v119, v116
	s_waitcnt vmcnt(2)
	v_lshlrev_b32_e32 v196, 16, v120
	v_and_b32_e32 v197, 0xffff0000, v120
	v_add_f32_e32 v116, v136, v116
	v_lshlrev_b32_e32 v190, 16, v121
	v_and_b32_e32 v191, 0xffff0000, v121
	v_pk_mul_f32 v[120:121], v[196:197], v[196:197]
	v_add_f32_e32 v116, v137, v116
	v_add_f32_e32 v116, v120, v116
	v_pk_mul_f32 v[192:193], v[190:191], v[190:191]
	v_add_f32_e32 v116, v121, v116
	v_lshlrev_b32_e32 v170, 16, v122
	v_and_b32_e32 v171, 0xffff0000, v122
	v_add_f32_e32 v116, v192, v116
	v_lshlrev_b32_e32 v138, 16, v123
	v_and_b32_e32 v139, 0xffff0000, v123
	v_pk_mul_f32 v[122:123], v[170:171], v[170:171]
	v_add_f32_e32 v116, v193, v116
	v_add_f32_e32 v116, v122, v116
	v_pk_mul_f32 v[140:141], v[138:139], v[138:139]
	v_add_f32_e32 v116, v123, v116
	s_waitcnt vmcnt(1)
	v_lshlrev_b32_e32 v78, 16, v91
	v_and_b32_e32 v79, 0xffff0000, v91
	v_lshlrev_b32_e32 v82, 16, v90
	v_and_b32_e32 v83, 0xffff0000, v90
	v_lshlrev_b32_e32 v90, 16, v88
	v_and_b32_e32 v91, 0xffff0000, v88
	v_add_f32_e32 v116, v140, v116
	v_pk_mul_f32 v[132:133], v[90:91], v[90:91]
	v_add_f32_e32 v116, v141, v116
	v_lshlrev_b32_e32 v86, 16, v89
	v_and_b32_e32 v87, 0xffff0000, v89
	v_add_f32_e32 v116, v132, v116
	v_pk_mul_f32 v[128:129], v[86:87], v[86:87]
	v_add_f32_e32 v116, v133, v116
	v_add_f32_e32 v116, v128, v116
	v_pk_mul_f32 v[126:127], v[82:83], v[82:83]
	v_add_f32_e32 v116, v129, v116
	v_add_f32_e32 v116, v126, v116
	v_pk_mul_f32 v[94:95], v[78:79], v[78:79]
	v_add_f32_e32 v116, v127, v116
	s_waitcnt vmcnt(0)
	v_lshlrev_b32_e32 v88, 16, v112
	v_and_b32_e32 v89, 0xffff0000, v112
	v_add_f32_e32 v94, v94, v116
	v_lshlrev_b32_e32 v84, 16, v113
	v_and_b32_e32 v85, 0xffff0000, v113
	v_pk_mul_f32 v[112:113], v[88:89], v[88:89]
	v_add_f32_e32 v94, v95, v94
	v_add_f32_e32 v94, v112, v94
	v_pk_mul_f32 v[130:131], v[84:85], v[84:85]
	v_add_f32_e32 v94, v113, v94
	v_lshlrev_b32_e32 v80, 16, v114
	v_and_b32_e32 v81, 0xffff0000, v114
	v_add_f32_e32 v94, v130, v94
	v_lshlrev_b32_e32 v76, 16, v115
	v_and_b32_e32 v77, 0xffff0000, v115
	v_pk_mul_f32 v[114:115], v[80:81], v[80:81]
	v_add_f32_e32 v94, v131, v94
	v_add_f32_e32 v94, v114, v94
	v_pk_mul_f32 v[124:125], v[76:77], v[76:77]
	v_add_f32_e32 v94, v115, v94
	v_add_f32_e32 v94, v124, v94
	v_add_f32_e32 v95, v125, v94
	ds_bpermute_b32 v112, v202, v95
	v_mov_b64_e32 v[120:121], s[2:3]
	v_or_b32_e32 v122, s4, v148
	v_cos_f32_e32 v71, v75
	v_sin_f32_e32 v75, v75
	s_waitcnt lgkmcnt(0)
	v_add_f32_e32 v95, v95, v112
	v_fmamk_f32 v95, v95, 0x3c800000, v186
	v_rsq_f32_e32 v112, v95
	v_mul_f32_e32 v94, v92, v182
	v_mul_f32_e32 v95, v93, v182
	v_cos_f32_e32 v92, v94
	v_mul_f32_e32 v128, 0x3e38aa3b, v112
	v_add_u32_e32 v112, s4, v177
	v_mad_i64_i32 v[112:113], s[2:3], v112, s10, v[120:121]
	v_mad_i64_i32 v[120:121], s[2:3], v122, s10, v[120:121]
	v_lshl_add_u64 v[112:113], v[112:113], 0, s[6:7]
	v_lshl_add_u64 v[120:121], v[120:121], 0, s[6:7]
	v_lshl_add_u64 v[116:117], v[112:113], 0, v[144:145]
	v_lshl_add_u64 v[124:125], v[112:113], 0, v[144:145]
	global_load_dwordx4 v[112:115], v[116:117], off offset:2064
	s_nop 0
	global_load_dwordx4 v[116:119], v[116:117], off offset:2048
	v_pk_mul_f32 v[36:37], v[36:37], v[128:129] op_sel_hi:[1,0]
	global_load_dwordx4 v[120:123], v[124:125], off offset:2560
	v_pk_mul_f32 v[44:45], v[44:45], v[128:129] op_sel_hi:[1,0]
	global_load_dwordx4 v[124:127], v[124:125], off offset:2576
	v_pk_mul_f32 v[36:37], v[36:37], v[196:197]
	v_pk_mul_f32 v[38:39], v[38:39], v[128:129] op_sel_hi:[1,0]
	v_pk_mul_f32 v[18:19], v[18:19], v[128:129] op_sel_hi:[1,0]
	v_pk_mul_f32 v[44:45], v[44:45], v[194:195]
	v_pk_mul_f32 v[46:47], v[46:47], v[128:129] op_sel_hi:[1,0]
	v_pk_mul_f32 v[38:39], v[38:39], v[190:191]
	v_pk_mul_f32 v[32:33], v[32:33], v[128:129] op_sel_hi:[1,0]
	v_pk_mul_f32 v[18:19], v[18:19], v[76:77]
	v_pk_mul_f32 v[76:77], v[48:49], v[36:37]
	v_pk_mul_f32 v[36:37], v[50:51], v[36:37]
	v_pk_mul_f32 v[46:47], v[46:47], v[172:173]
	v_pk_mul_f32 v[40:41], v[40:41], v[128:129] op_sel_hi:[1,0]
	v_pk_mul_f32 v[32:33], v[32:33], v[170:171]
	v_pk_mul_f32 v[34:35], v[34:35], v[128:129] op_sel_hi:[1,0]
	v_pk_fma_f32 v[76:77], v[50:51], v[44:45], v[76:77]
	v_pk_fma_f32 v[36:37], v[48:49], v[44:45], v[36:37] neg_lo:[0,0,1] neg_hi:[0,0,1]
	v_pk_mul_f32 v[44:45], v[52:53], v[38:39]
	v_pk_mul_f32 v[38:39], v[54:55], v[38:39]
	v_pk_mul_f32 v[40:41], v[40:41], v[142:143]
	v_pk_mul_f32 v[42:43], v[42:43], v[128:129] op_sel_hi:[1,0]
	v_pk_mul_f32 v[34:35], v[34:35], v[138:139]
	v_pk_mul_f32 v[20:21], v[20:21], v[128:129] op_sel_hi:[1,0]
	v_pk_fma_f32 v[44:45], v[54:55], v[46:47], v[44:45]
	v_pk_fma_f32 v[38:39], v[52:53], v[46:47], v[38:39] neg_lo:[0,0,1] neg_hi:[0,0,1]
	v_pk_mul_f32 v[46:47], v[56:57], v[32:33]
	v_pk_mul_f32 v[32:33], v[58:59], v[32:33]
	v_sin_f32_e32 v94, v94
	v_cos_f32_e32 v93, v95
	v_sin_f32_e32 v95, v95
	v_pk_mul_f32 v[42:43], v[42:43], v[134:135]
	v_pk_mul_f32 v[28:29], v[28:29], v[128:129] op_sel_hi:[1,0]
	v_pk_mul_f32 v[20:21], v[20:21], v[88:89]
	v_pk_mul_f32 v[22:23], v[22:23], v[128:129] op_sel_hi:[1,0]
	v_pk_fma_f32 v[46:47], v[58:59], v[40:41], v[46:47]
	v_pk_fma_f32 v[32:33], v[56:57], v[40:41], v[32:33] neg_lo:[0,0,1] neg_hi:[0,0,1]
	v_pk_mul_f32 v[40:41], v[60:61], v[34:35]
	v_pk_mul_f32 v[34:35], v[62:63], v[34:35]
	v_pk_mul_f32 v[28:29], v[28:29], v[90:91]
	v_pk_mul_f32 v[30:31], v[30:31], v[128:129] op_sel_hi:[1,0]
	v_pk_mul_f32 v[22:23], v[22:23], v[84:85]
	v_pk_mul_f32 v[16:17], v[16:17], v[128:129] op_sel_hi:[1,0]
	v_pk_fma_f32 v[40:41], v[62:63], v[42:43], v[40:41]
	v_pk_fma_f32 v[34:35], v[60:61], v[42:43], v[34:35] neg_lo:[0,0,1] neg_hi:[0,0,1]
	v_pk_mul_f32 v[42:43], v[64:65], v[20:21]
	v_pk_mul_f32 v[20:21], v[68:69], v[20:21]
	v_pk_mul_f32 v[30:31], v[30:31], v[86:87]
	v_pk_mul_f32 v[24:25], v[24:25], v[128:129] op_sel_hi:[1,0]
	v_pk_mul_f32 v[16:17], v[16:17], v[80:81]
	v_pk_fma_f32 v[42:43], v[68:69], v[28:29], v[42:43]
	v_pk_fma_f32 v[20:21], v[64:65], v[28:29], v[20:21] neg_lo:[0,0,1] neg_hi:[0,0,1]
	v_pk_mul_f32 v[28:29], v[66:67], v[22:23]
	v_pk_mul_f32 v[22:23], v[72:73], v[22:23]
	v_pk_mul_f32 v[24:25], v[24:25], v[82:83]
	v_pk_mul_f32 v[26:27], v[26:27], v[128:129] op_sel_hi:[1,0]
	v_pk_fma_f32 v[28:29], v[72:73], v[30:31], v[28:29]
	v_pk_fma_f32 v[22:23], v[66:67], v[30:31], v[22:23] neg_lo:[0,0,1] neg_hi:[0,0,1]
	v_pk_mul_f32 v[30:31], v[70:71], v[16:17]
	v_pk_mul_f32 v[16:17], v[74:75], v[16:17]
	v_pk_mul_f32 v[26:27], v[26:27], v[78:79]
	v_pk_fma_f32 v[30:31], v[74:75], v[24:25], v[30:31]
	v_pk_fma_f32 v[16:17], v[70:71], v[24:25], v[16:17] neg_lo:[0,0,1] neg_hi:[0,0,1]
	v_pk_mul_f32 v[24:25], v[92:93], v[18:19]
	v_pk_mul_f32 v[18:19], v[94:95], v[18:19]
	v_pk_fma_f32 v[24:25], v[94:95], v[26:27], v[24:25]
	v_pk_fma_f32 v[18:19], v[92:93], v[26:27], v[18:19] neg_lo:[0,0,1] neg_hi:[0,0,1]
	v_cvt_pk_bf16_f32 v142, v30, v31
	s_cmpk_eq_i32 s0, 0x1f80
	v_mov_b32_e32 v30, v145
	v_mov_b32_e32 v31, v145
	v_cvt_pk_bf16_f32 v128, v36, v37
	v_cvt_pk_bf16_f32 v129, v38, v39
	v_cvt_pk_bf16_f32 v130, v32, v33
	v_cvt_pk_bf16_f32 v131, v34, v35
	v_cvt_pk_bf16_f32 v132, v76, v77
	v_cvt_pk_bf16_f32 v133, v44, v45
	v_cvt_pk_bf16_f32 v134, v46, v47
	v_cvt_pk_bf16_f32 v135, v40, v41
	v_cvt_pk_bf16_f32 v136, v20, v21
	v_cvt_pk_bf16_f32 v137, v22, v23
	v_cvt_pk_bf16_f32 v138, v16, v17
	v_cvt_pk_bf16_f32 v139, v18, v19
	v_cvt_pk_bf16_f32 v140, v42, v43
	v_cvt_pk_bf16_f32 v141, v28, v29
	v_cvt_pk_bf16_f32 v143, v24, v25
	s_cselect_b32 s22, 3, 2
	v_writelane_b32 v243, s11, 60
	s_and_b32 s23, s11, 0xffffff00
	s_mov_b32 s1, s7
	v_mov_b32_e32 v16, v145
	v_mov_b32_e32 v17, v145
	v_mov_b32_e32 v18, v145
	v_mov_b32_e32 v19, v145
	v_mov_b32_e32 v20, v145
	v_mov_b32_e32 v21, v145
	v_mov_b32_e32 v22, v145
	v_mov_b32_e32 v23, v145
	v_mov_b32_e32 v24, v145
	v_mov_b32_e32 v25, v145
	v_mov_b32_e32 v26, v145
	v_mov_b32_e32 v27, v145
	v_mov_b32_e32 v28, v145
	v_mov_b32_e32 v29, v145
	v_mov_b64_e32 v[46:47], v[30:31]
	v_mov_b64_e32 v[62:63], v[30:31]
	v_mov_b64_e32 v[78:79], v[30:31]
	v_ashrrev_i32_e32 v161, 31, v160
	v_ashrrev_i32_e32 v167, 31, v166
	s_mov_b32 s33, 0
	v_readfirstlane_b32 s25, v165
	s_add_i32 s23, s23, 0xfe80
	s_addk_i32 s24, 0xff80
	v_lshl_add_u64 v[170:171], v[156:157], 0, s[6:7]
	v_writelane_b32 v243, s0, 50
	v_lshl_add_u64 v[172:173], v[158:159], 0, s[6:7]
	v_mov_b64_e32 v[44:45], v[28:29]
	v_mov_b64_e32 v[42:43], v[26:27]
	v_mov_b64_e32 v[40:41], v[24:25]
	v_mov_b64_e32 v[38:39], v[22:23]
	v_mov_b64_e32 v[36:37], v[20:21]
	v_mov_b64_e32 v[34:35], v[18:19]
	v_mov_b64_e32 v[32:33], v[16:17]
	v_mov_b64_e32 v[60:61], v[28:29]
	v_mov_b64_e32 v[58:59], v[26:27]
	v_mov_b64_e32 v[56:57], v[24:25]
	v_mov_b64_e32 v[54:55], v[22:23]
	v_mov_b64_e32 v[52:53], v[20:21]
	v_mov_b64_e32 v[50:51], v[18:19]
	v_mov_b64_e32 v[48:49], v[16:17]
	v_mov_b64_e32 v[76:77], v[28:29]
	v_mov_b64_e32 v[74:75], v[26:27]
	v_mov_b64_e32 v[72:73], v[24:25]
	v_mov_b64_e32 v[70:71], v[22:23]
	v_mov_b64_e32 v[68:69], v[20:21]
	v_mov_b64_e32 v[66:67], v[18:19]
	v_mov_b64_e32 v[64:65], v[16:17]
	v_mov_b32_e32 v187, 0
	v_mov_b32_e32 v188, 0
	s_waitcnt vmcnt(2)
	ds_write_b128 v179, v[116:119]
	ds_write_b128 v179, v[112:115] offset:16
	s_waitcnt vmcnt(1)
	ds_write_b16 v153, v120 offset:18432
	ds_write_b16_d16_hi v153, v120 offset:18696
	ds_write_b16 v153, v121 offset:18960
	ds_write_b16_d16_hi v153, v121 offset:19224
	ds_write_b16 v153, v122 offset:19488
	ds_write_b16_d16_hi v153, v122 offset:19752
	ds_write_b16 v153, v123 offset:20016
	ds_write_b16_d16_hi v153, v123 offset:20280
	s_waitcnt vmcnt(0)
	ds_write_b16 v153, v124 offset:20544
	ds_write_b16_d16_hi v153, v124 offset:20808
	ds_write_b16 v153, v125 offset:21072
	ds_write_b16_d16_hi v153, v125 offset:21336
	ds_write_b16 v153, v126 offset:21600
	ds_write_b16_d16_hi v153, v126 offset:21864
	ds_write_b16 v153, v127 offset:22128
	ds_write_b16_d16_hi v153, v127 offset:22392
	s_waitcnt lgkmcnt(0)
	s_barrier
	v_writelane_b32 v243, s1, 51
.LBB0_1168:
	s_add_i32 s0, s25, 1
	s_cmp_eq_u32 s0, 2
	s_cselect_b32 s26, s22, s0
	s_cmp_lt_i32 s26, 5
	s_cselect_b64 s[12:13], -1, 0
	s_cmp_gt_i32 s26, 4
	s_cselect_b64 s[10:11], -1, 0
	s_and_b64 vcc, exec, s[10:11]
	s_cbranch_vccnz .LBB0_1170
	s_lshl_b32 s0, s26, 7
	s_cmp_lt_i32 s26, 3
	s_cselect_b32 s1, s24, s23
	s_add_i32 s2, s1, s0
	v_add_u32_e32 v80, s2, v177
	s_movk_i32 s3, 0xc00
	v_mad_i64_i32 v[80:81], s[0:1], v80, s3, v[170:171]
	global_load_dwordx4 v[112:115], v[80:81], off offset:2064
	global_load_dwordx4 v[116:119], v[80:81], off offset:2048
	s_nop 0
	s_nop 0
	global_load_dwordx4 v[120:123], v[80:81], off offset:2560
	global_load_dwordx4 v[124:127], v[80:81], off offset:2576

.Lat_m1_nodiag:
	v_add_f32_e32 v189, v80, v81
	v_add_f32_e32 v190, v82, v83
	v_add_f32_e32 v191, v84, v85
	v_add_f32_e32 v192, v86, v87
	v_add_f32_e32 v193, v88, v89
	v_add_f32_e32 v194, v90, v91
	v_add_f32_e32 v195, v92, v93
	v_add_f32_e32 v196, v94, v95
	v_cvt_pk_bf16_f32 v80, v80, v81
	v_cvt_pk_bf16_f32 v81, v82, v83
	v_cvt_pk_bf16_f32 v82, v84, v85
	v_cvt_pk_bf16_f32 v83, v86, v87
	v_cvt_pk_bf16_f32 v84, v88, v89
	v_cvt_pk_bf16_f32 v85, v90, v91
	v_cvt_pk_bf16_f32 v86, v92, v93
	v_cvt_pk_bf16_f32 v87, v94, v95
	v_add_f32_e32 v189, v189, v190
	v_add_f32_e32 v191, v191, v192
	v_add_f32_e32 v193, v193, v194
	v_add_f32_e32 v195, v195, v196
	v_add_f32_e32 v189, v189, v191
	v_add_f32_e32 v193, v193, v195
	v_add_f32_e32 v189, v189, v193
	v_add_f32_e32 v187, v187, v189
	s_waitcnt lgkmcnt(4)
	v_mfma_f32_32x32x16_bf16 v[32:47], v[220:223], v[80:83], v[32:47]
	v_mfma_f32_32x32x16_bf16 v[16:31], v[224:227], v[80:83], v[16:31]
	v_mfma_f32_32x32x16_bf16 v[32:47], v[228:231], v[84:87], v[32:47]
	v_mfma_f32_32x32x16_bf16 v[16:31], v[232:235], v[84:87], v[16:31]
	s_add_i32 s70, s70, 1
	s_cmp_le_u32 s70, s71
	s_cbranch_scc1 .Lat_m1_tile
	s_branch .Lpad_end
	s_nop 0
	s_nop 0
	s_nop 0
	s_nop 0
	s_nop 0
	s_nop 0
	s_nop 0
	s_nop 0
	s_nop 0
	s_nop 0
	s_nop 0
	s_nop 0
	s_nop 0
	s_nop 0
	s_nop 0
	s_nop 0
	s_nop 0
	s_nop 0
	s_nop 0
	s_nop 0
	s_nop 0
	s_nop 0
	s_nop 0
	s_nop 0
	s_nop 0
	s_nop 0
	s_nop 0
	s_nop 0
	s_nop 0
	s_nop 0
	s_nop 0
	s_nop 0
	s_nop 0
	s_nop 0
	s_nop 0
	s_nop 0
	s_nop 0
	s_nop 0
	s_nop 0
	s_nop 0
	s_nop 0
	s_nop 0
	s_nop 0
	s_nop 0
	s_nop 0
	s_nop 0
	s_nop 0
	s_nop 0
	s_nop 0
	s_nop 0
	s_nop 0
	s_nop 0
	s_nop 0
	s_nop 0
	s_nop 0
	s_nop 0
	s_nop 0
	s_nop 0
	s_nop 0
	s_nop 0
	s_nop 0
	s_nop 0
	s_nop 0
	s_nop 0
	s_nop 0
	s_nop 0
	s_nop 0
	s_nop 0
	s_nop 0
	s_nop 0
	s_nop 0
	s_nop 0
	s_nop 0
	s_nop 0
	s_nop 0
	s_nop 0
	s_nop 0
	s_nop 0
	s_nop 0
	s_nop 0
	s_nop 0
	s_nop 0
	s_nop 0
	s_nop 0
	s_nop 0
	s_nop 0
	s_nop 0
	s_nop 0
	s_nop 0
	s_nop 0
	s_nop 0
	s_nop 0
	s_nop 0
	s_nop 0
	s_nop 0
	s_nop 0
	s_nop 0
	s_nop 0
	s_nop 0
	s_nop 0
	s_nop 0
	s_nop 0
	s_nop 0
	s_nop 0
	s_nop 0
	s_nop 0
	s_nop 0
	s_nop 0
	s_nop 0
	s_nop 0
	s_nop 0
	s_nop 0
	s_nop 0
	s_nop 0
	s_nop 0
	s_nop 0
	s_nop 0
	s_nop 0
	s_nop 0
	s_nop 0
	s_nop 0
	s_nop 0
	s_nop 0
	s_nop 0
	s_nop 0
	s_nop 0
	s_nop 0
	s_nop 0
	s_nop 0
	s_nop 0
	s_nop 0
	s_nop 0
	s_nop 0
	s_nop 0
	s_nop 0
	s_nop 0
	s_nop 0
	s_nop 0
	s_nop 0
	s_nop 0
	s_nop 0
	s_nop 0
	s_nop 0
	s_nop 0
	s_nop 0
	s_nop 0
	s_nop 0
	s_nop 0
	s_nop 0
	s_nop 0
	s_nop 0
	s_nop 0
	s_nop 0
	s_nop 0
	s_nop 0
	s_nop 0
	s_nop 0
	s_nop 0
	s_nop 0
	s_nop 0
	s_nop 0
	s_nop 0
	s_nop 0
	s_nop 0
	s_nop 0
	s_nop 0
	s_nop 0
	s_nop 0
	s_nop 0
	s_nop 0
	s_nop 0
	s_nop 0
	s_nop 0
	s_nop 0
	s_nop 0
	s_nop 0
	s_nop 0
	s_nop 0
	s_nop 0
	s_nop 0
	s_nop 0
	s_nop 0
	s_nop 0
	s_nop 0
	s_nop 0
	s_nop 0
	s_nop 0
	s_nop 0
	s_nop 0
	s_nop 0
	s_nop 0
	s_nop 0
	s_nop 0
	s_nop 0
	s_nop 0
	s_nop 0
	s_nop 0
	s_nop 0
	s_nop 0
	s_nop 0
	s_nop 0
	s_nop 0
	s_nop 0
	s_nop 0
	s_nop 0
	s_nop 0
	s_nop 0
	s_nop 0
	s_nop 0
	s_nop 0
	s_nop 0
	s_nop 0
	s_nop 0
	s_nop 0
	s_nop 0
	s_nop 0
	s_nop 0
	s_nop 0
	s_nop 0
	s_nop 0
	s_nop 0
	s_nop 0
	s_nop 0
	s_nop 0
	s_nop 0
.Lpad_end:
	s_xor_b32 s33, s33, 1
	s_and_b64 vcc, exec, s[12:13]
	s_cbranch_vccz .LBB0_1200
	s_mul_i32 s0, s33, 0x8a00
	s_add_i32 s0, s0, 0
	v_add3_u32 v80, s0, v178, v144
	s_waitcnt vmcnt(2)
	ds_write_b128 v80, v[116:119]
	ds_write_b128 v80, v[112:115] offset:16
	v_lshl_add_u32 v80, v152, 1, s0
	s_waitcnt vmcnt(1)
	ds_write_b16 v80, v120 offset:18432
	ds_write_b16_d16_hi v80, v120 offset:18696
	ds_write_b16 v80, v121 offset:18960
	ds_write_b16_d16_hi v80, v121 offset:19224
	ds_write_b16 v80, v122 offset:19488
	ds_write_b16_d16_hi v80, v122 offset:19752
	ds_write_b16 v80, v123 offset:20016
	ds_write_b16_d16_hi v80, v123 offset:20280
	s_waitcnt vmcnt(0)
	ds_write_b16 v80, v124 offset:20544
	ds_write_b16_d16_hi v80, v124 offset:20808
	ds_write_b16 v80, v125 offset:21072
	ds_write_b16_d16_hi v80, v125 offset:21336
	ds_write_b16 v80, v126 offset:21600
	ds_write_b16_d16_hi v80, v126 offset:21864
	ds_write_b16 v80, v127 offset:22128
	ds_write_b16_d16_hi v80, v127 offset:22392
